# v44 plus s_setprio 1 on the attention compute segments
# speedup vs baseline: 1.0079x; 1.0009x over previous
; __device__ __forceinline__ void finishSM2(f32x16& p0, f32x16& p1, float alpha, float& l_reg, bf16x8& pa0, bf16x8& pa1, bf16x8& pa2, bf16x8& pa3) {
; #pragma unroll
;   for (int r = 0; r < 16; ++r) p1[r] = __builtin_amdgcn_exp2f(p1[r]);
;   float ps = 0;
; #pragma unroll
;   for (int r = 0; r < 16; ++r) ps += p0[r];
; #pragma unroll
;   for (int r = 0; r < 16; ++r) ps += p1[r];
;   { auto rr = __builtin_amdgcn_permlane32_swap(__float_as_uint(ps), __float_as_uint(ps), false, false);
;     ps = __uint_as_float(rr[0]) + __uint_as_float(rr[1]); }
;   l_reg = l_reg * alpha + ps;
;     ...
;   PK8(p0, 0, pa0); PK8(p0, 8, pa1); PK8(p1, 0, pa2); PK8(p1, 8, pa3);
;     ...
; }
; __device__ __forceinline__ void kload12(bf16x8* kf, const LAS char* Ks, int r32, int hi) {
;   const LAS char* kb = Ks + hi * 1024 + r32 * 16;
; #pragma unroll
;   for (int d0 = 0; d0 < 6; ++d0) { kf[2 * d0] = *(const LAS bf16x8*)(kb + d0 * 2048); kf[2 * d0 + 1] = *(const LAS bf16x8*)(kb + d0 * 2048 + 512); }
; }
; __device__ __forceinline__ void qkt3(f32x16& p0, f32x16& p1, const bf16x8* kf, const bf16x8* qr) {
;   p0 = f32x16{}; p1 = f32x16{};
; #pragma unroll
;   for (int d0 = 0; d0 < 6; ++d0) {
;     p0 = __builtin_amdgcn_mfma_f32_32x32x16_bf16(kf[2 * d0], qr[d0], p0, 0, 0, 0);
;     p1 = __builtin_amdgcn_mfma_f32_32x32x16_bf16(kf[2 * d0 + 1], qr[d0], p1, 0, 0, 0); }
; }
; __device__ __forceinline__ void vload16(s16x4* vf, int vb) {
;   vf[0] = tr_read<0>(vb); vf[1] = tr_read<512>(vb); vf[2] = tr_read<1024>(vb); vf[3] = tr_read<1536>(vb);
;   vf[4] = tr_read<2048>(vb); vf[5] = tr_read<2560>(vb); vf[6] = tr_read<3072>(vb); vf[7] = tr_read<3584>(vb);
;   vf[8] = tr_read<4096>(vb); vf[9] = tr_read<4608>(vb); vf[10] = tr_read<5120>(vb); vf[11] = tr_read<5632>(vb);
;   vf[12] = tr_read<6144>(vb); vf[13] = tr_read<6656>(vb); vf[14] = tr_read<7168>(vb); vf[15] = tr_read<7680>(vb);
; }
; __device__ __forceinline__ void pv3(f32x16* o, const s16x4* vf, bf16x8 pa0, bf16x8 pa1, bf16x8 pa2, bf16x8 pa3) {
;     ...
;   o[0] = __builtin_amdgcn_mfma_f32_32x32x16_bf16(pa0, PKV(0), o[0], 0, 0, 0);
;   o[1] = __builtin_amdgcn_mfma_f32_32x32x16_bf16(pa0, PKV(8), o[1], 0, 0, 0);
;   o[0] = __builtin_amdgcn_mfma_f32_32x32x16_bf16(pa1, PKV(2), o[0], 0, 0, 0);
;   o[1] = __builtin_amdgcn_mfma_f32_32x32x16_bf16(pa1, PKV(10), o[1], 0, 0, 0);
;   o[0] = __builtin_amdgcn_mfma_f32_32x32x16_bf16(pa2, PKV(4), o[0], 0, 0, 0);
.Lwd_a:
	s_barrier
	s_waitcnt lgkmcnt(0)
	s_setprio 1
	v_mfma_f32_32x32x16_bf16 v[80:95], v[48:51], v[116:119], v[238:253]
	v_exp_f32_e32 v64, v64
	v_add_f32_e32 v213, v32, v213
	ds_read_b64_tr_b16 v[148:149], v217 offset:0
	v_exp_f32_e32 v65, v65
	v_add_f32_e32 v213, v33, v213
	ds_read_b64_tr_b16 v[150:151], v217 offset:512
	v_mfma_f32_32x32x16_bf16 v[48:63], v[52:55], v[116:119], v[238:253]
	v_exp_f32_e32 v66, v66
	v_add_f32_e32 v213, v34, v213
	ds_read_b64_tr_b16 v[140:141], v217 offset:1024
	v_exp_f32_e32 v67, v67
	v_add_f32_e32 v213, v35, v213
	ds_read_b64_tr_b16 v[142:143], v217 offset:1536
	v_mfma_f32_32x32x16_bf16 v[80:95], v[188:191], v[112:115], v[80:95]
	v_exp_f32_e32 v68, v68
	v_add_f32_e32 v213, v36, v213
	ds_read_b64_tr_b16 v[132:133], v217 offset:2048
	v_exp_f32_e32 v69, v69
	v_add_f32_e32 v213, v37, v213
	ds_read_b64_tr_b16 v[134:135], v217 offset:2560
	v_mfma_f32_32x32x16_bf16 v[48:63], v[184:187], v[112:115], v[48:63]
	v_exp_f32_e32 v70, v70
	v_add_f32_e32 v213, v38, v213
	ds_read_b64_tr_b16 v[124:125], v217 offset:3072
	v_exp_f32_e32 v71, v71
	v_add_f32_e32 v213, v39, v213
	ds_read_b64_tr_b16 v[126:127], v217 offset:3584
	v_mfma_f32_32x32x16_bf16 v[80:95], v[180:183], v[108:111], v[80:95]
	v_exp_f32_e32 v72, v72
	v_add_f32_e32 v213, v40, v213
	ds_read_b64_tr_b16 v[144:145], v217 offset:4096
	v_exp_f32_e32 v73, v73
	v_add_f32_e32 v213, v41, v213
	ds_read_b64_tr_b16 v[146:147], v217 offset:4608
	v_mfma_f32_32x32x16_bf16 v[48:63], v[176:179], v[108:111], v[48:63]
	v_exp_f32_e32 v74, v74
	v_add_f32_e32 v213, v42, v213
	ds_read_b64_tr_b16 v[136:137], v217 offset:5120
	v_exp_f32_e32 v75, v75
	v_add_f32_e32 v213, v43, v213
	ds_read_b64_tr_b16 v[138:139], v217 offset:5632
	v_mfma_f32_32x32x16_bf16 v[80:95], v[172:175], v[104:107], v[80:95]
	v_exp_f32_e32 v76, v76
	v_add_f32_e32 v213, v44, v213
	ds_read_b64_tr_b16 v[128:129], v217 offset:6144
	v_exp_f32_e32 v77, v77
	v_add_f32_e32 v213, v45, v213
	ds_read_b64_tr_b16 v[130:131], v217 offset:6656
	v_mfma_f32_32x32x16_bf16 v[48:63], v[168:171], v[104:107], v[48:63]
	v_exp_f32_e32 v78, v78
	v_add_f32_e32 v213, v46, v213
	ds_read_b64_tr_b16 v[120:121], v217 offset:7168
	v_exp_f32_e32 v79, v79
	v_add_f32_e32 v213, v47, v213
	ds_read_b64_tr_b16 v[122:123], v217 offset:7680
	v_mfma_f32_32x32x16_bf16 v[80:95], v[164:167], v[100:103], v[80:95]
	v_add_f32_e32 v237, v64, v65
	v_add_f32_e32 v237, v66, v237
	v_add_f32_e32 v237, v67, v237
	v_add_f32_e32 v237, v68, v237
	v_add_f32_e32 v237, v69, v237
	v_add_f32_e32 v237, v70, v237
	v_add_f32_e32 v237, v71, v237
	v_add_f32_e32 v237, v72, v237
	v_mfma_f32_32x32x16_bf16 v[48:63], v[160:163], v[100:103], v[48:63]
	v_add_f32_e32 v237, v73, v237
	v_add_f32_e32 v237, v74, v237
	v_add_f32_e32 v237, v75, v237
	v_add_f32_e32 v237, v76, v237
	v_add_f32_e32 v237, v77, v237
	v_add_f32_e32 v237, v78, v237
	v_add_f32_e32 v237, v79, v237
	v_add_f32_e32 v213, v237, v213
	v_mfma_f32_32x32x16_bf16 v[80:95], v[156:159], v[96:99], v[80:95]
	v_cvt_pk_bf16_f32 v32, v32, v33
	v_cvt_pk_bf16_f32 v33, v34, v35
	v_cvt_pk_bf16_f32 v34, v36, v37
	v_cvt_pk_bf16_f32 v35, v38, v39
	v_cvt_pk_bf16_f32 v36, v40, v41
	v_cvt_pk_bf16_f32 v37, v42, v43
	v_cvt_pk_bf16_f32 v38, v44, v45
	v_cvt_pk_bf16_f32 v39, v46, v47
	v_mfma_f32_32x32x16_bf16 v[48:63], v[152:155], v[96:99], v[48:63]
	v_cvt_pk_bf16_f32 v64, v64, v65
	v_cvt_pk_bf16_f32 v65, v66, v67
	v_cvt_pk_bf16_f32 v66, v68, v69
	v_cvt_pk_bf16_f32 v67, v70, v71
	v_cvt_pk_bf16_f32 v68, v72, v73
	v_cvt_pk_bf16_f32 v69, v74, v75
	v_cvt_pk_bf16_f32 v70, v76, v77
	v_cvt_pk_bf16_f32 v71, v78, v79
	s_waitcnt lgkmcnt(0)
	v_mfma_f32_32x32x16_bf16 v[0:15], v[32:35], v[148:151], v[0:15]
	v_exp_f32_e32 v40, v88
	v_exp_f32_e32 v41, v89
	v_mfma_f32_32x32x16_bf16 v[16:31], v[32:35], v[144:147], v[16:31]
	v_exp_f32_e32 v42, v90
	v_exp_f32_e32 v43, v91
	v_mfma_f32_32x32x16_bf16 v[0:15], v[36:39], v[140:143], v[0:15]
	v_exp_f32_e32 v44, v92
	v_exp_f32_e32 v45, v93
	v_mfma_f32_32x32x16_bf16 v[16:31], v[36:39], v[136:139], v[16:31]
	v_exp_f32_e32 v46, v94
	v_exp_f32_e32 v47, v95
	v_mfma_f32_32x32x16_bf16 v[0:15], v[64:67], v[132:135], v[0:15]
	v_exp_f32_e32 v32, v80
	v_exp_f32_e32 v33, v81
	v_mfma_f32_32x32x16_bf16 v[16:31], v[64:67], v[128:131], v[16:31]
	v_exp_f32_e32 v34, v82
	v_exp_f32_e32 v35, v83
	v_mfma_f32_32x32x16_bf16 v[0:15], v[68:71], v[124:127], v[0:15]
	v_exp_f32_e32 v36, v84
	v_exp_f32_e32 v37, v85
	v_mfma_f32_32x32x16_bf16 v[16:31], v[68:71], v[120:123], v[16:31]
	v_exp_f32_e32 v38, v86
	v_exp_f32_e32 v39, v87
	s_setprio 0
	s_barrier
	v_max3_f32 v215, v80, v81, v82
	v_max3_f32 v215, v215, v83, v84
	v_max3_f32 v215, v215, v85, v86
	v_max3_f32 v215, v215, v87, v88
	v_max3_f32 v215, v215, v89, v90
	v_max3_f32 v215, v215, v91, v92
	v_max3_f32 v215, v215, v93, v94
	v_max3_f32 v215, v215, v95, v48
	v_max3_f32 v215, v215, v49, v50
	v_max3_f32 v215, v215, v51, v52
	v_max3_f32 v215, v215, v53, v54
	v_max3_f32 v215, v215, v55, v56
	v_max3_f32 v215, v215, v57, v58
	v_max3_f32 v215, v215, v59, v60
	v_max3_f32 v215, v215, v61, v62
	v_max_f32_e32 v215, v215, v63
	v_cmp_nge_f32_e32 vcc, s23, v215
	s_nop 3
	s_cmp_lg_u64 vcc, 0
	s_cbranch_scc1 .Lrare_a

; __device__ __forceinline__ void finishSM2(f32x16& p0, f32x16& p1, float alpha, float& l_reg, bf16x8& pa0, bf16x8& pa1, bf16x8& pa2, bf16x8& pa3) {
; #pragma unroll
;   for (int r = 0; r < 16; ++r) p1[r] = __builtin_amdgcn_exp2f(p1[r]);
;   float ps = 0;
; #pragma unroll
;   for (int r = 0; r < 16; ++r) ps += p0[r];
; #pragma unroll
;   for (int r = 0; r < 16; ++r) ps += p1[r];
;   { auto rr = __builtin_amdgcn_permlane32_swap(__float_as_uint(ps), __float_as_uint(ps), false, false);
;     ps = __uint_as_float(rr[0]) + __uint_as_float(rr[1]); }
;   l_reg = l_reg * alpha + ps;
;     ...
;   PK8(p0, 0, pa0); PK8(p0, 8, pa1); PK8(p1, 0, pa2); PK8(p1, 8, pa3);
;     ...
; }
; __device__ __forceinline__ void kload12(bf16x8* kf, const LAS char* Ks, int r32, int hi) {
;   const LAS char* kb = Ks + hi * 1024 + r32 * 16;
; #pragma unroll
;   for (int d0 = 0; d0 < 6; ++d0) { kf[2 * d0] = *(const LAS bf16x8*)(kb + d0 * 2048); kf[2 * d0 + 1] = *(const LAS bf16x8*)(kb + d0 * 2048 + 512); }
; }
; __device__ __forceinline__ void qkt3(f32x16& p0, f32x16& p1, const bf16x8* kf, const bf16x8* qr) {
;   p0 = f32x16{}; p1 = f32x16{};
; #pragma unroll
;   for (int d0 = 0; d0 < 6; ++d0) {
;     p0 = __builtin_amdgcn_mfma_f32_32x32x16_bf16(kf[2 * d0], qr[d0], p0, 0, 0, 0);
;     p1 = __builtin_amdgcn_mfma_f32_32x32x16_bf16(kf[2 * d0 + 1], qr[d0], p1, 0, 0, 0); }
; }
; __device__ __forceinline__ void vload16(s16x4* vf, int vb) {
;   vf[0] = tr_read<0>(vb); vf[1] = tr_read<512>(vb); vf[2] = tr_read<1024>(vb); vf[3] = tr_read<1536>(vb);
;   vf[4] = tr_read<2048>(vb); vf[5] = tr_read<2560>(vb); vf[6] = tr_read<3072>(vb); vf[7] = tr_read<3584>(vb);
;   vf[8] = tr_read<4096>(vb); vf[9] = tr_read<4608>(vb); vf[10] = tr_read<5120>(vb); vf[11] = tr_read<5632>(vb);
;   vf[12] = tr_read<6144>(vb); vf[13] = tr_read<6656>(vb); vf[14] = tr_read<7168>(vb); vf[15] = tr_read<7680>(vb);
; }
; __device__ __forceinline__ void pv3(f32x16* o, const s16x4* vf, bf16x8 pa0, bf16x8 pa1, bf16x8 pa2, bf16x8 pa3) {
;     ...
;   o[0] = __builtin_amdgcn_mfma_f32_32x32x16_bf16(pa0, PKV(0), o[0], 0, 0, 0);
;   o[1] = __builtin_amdgcn_mfma_f32_32x32x16_bf16(pa0, PKV(8), o[1], 0, 0, 0);
;   o[0] = __builtin_amdgcn_mfma_f32_32x32x16_bf16(pa1, PKV(2), o[0], 0, 0, 0);
;   o[1] = __builtin_amdgcn_mfma_f32_32x32x16_bf16(pa1, PKV(10), o[1], 0, 0, 0);
;   o[0] = __builtin_amdgcn_mfma_f32_32x32x16_bf16(pa2, PKV(4), o[0], 0, 0, 0);
.Lwd_b:
	s_barrier
	s_waitcnt lgkmcnt(0)
	s_setprio 1
	v_mfma_f32_32x32x16_bf16 v[80:95], v[64:67], v[116:119], v[238:253]
	v_exp_f32_e32 v48, v48
	v_add_f32_e32 v213, v32, v213
	ds_read_b64_tr_b16 v[148:149], v217 offset:0
	v_exp_f32_e32 v49, v49
	v_add_f32_e32 v213, v33, v213
	ds_read_b64_tr_b16 v[150:151], v217 offset:512
	v_mfma_f32_32x32x16_bf16 v[64:79], v[68:71], v[116:119], v[238:253]
	v_exp_f32_e32 v50, v50
	v_add_f32_e32 v213, v34, v213
	ds_read_b64_tr_b16 v[140:141], v217 offset:1024
	v_exp_f32_e32 v51, v51
	v_add_f32_e32 v213, v35, v213
	ds_read_b64_tr_b16 v[142:143], v217 offset:1536
	v_mfma_f32_32x32x16_bf16 v[80:95], v[188:191], v[112:115], v[80:95]
	v_exp_f32_e32 v52, v52
	v_add_f32_e32 v213, v36, v213
	ds_read_b64_tr_b16 v[132:133], v217 offset:2048
	v_exp_f32_e32 v53, v53
	v_add_f32_e32 v213, v37, v213
	ds_read_b64_tr_b16 v[134:135], v217 offset:2560
	v_mfma_f32_32x32x16_bf16 v[64:79], v[184:187], v[112:115], v[64:79]
	v_exp_f32_e32 v54, v54
	v_add_f32_e32 v213, v38, v213
	ds_read_b64_tr_b16 v[124:125], v217 offset:3072
	v_exp_f32_e32 v55, v55
	v_add_f32_e32 v213, v39, v213
	ds_read_b64_tr_b16 v[126:127], v217 offset:3584
	v_mfma_f32_32x32x16_bf16 v[80:95], v[180:183], v[108:111], v[80:95]
	v_exp_f32_e32 v56, v56
	v_add_f32_e32 v213, v40, v213
	ds_read_b64_tr_b16 v[144:145], v217 offset:4096
	v_exp_f32_e32 v57, v57
	v_add_f32_e32 v213, v41, v213
	ds_read_b64_tr_b16 v[146:147], v217 offset:4608
	v_mfma_f32_32x32x16_bf16 v[64:79], v[176:179], v[108:111], v[64:79]
	v_exp_f32_e32 v58, v58
	v_add_f32_e32 v213, v42, v213
	ds_read_b64_tr_b16 v[136:137], v217 offset:5120
	v_exp_f32_e32 v59, v59
	v_add_f32_e32 v213, v43, v213
	ds_read_b64_tr_b16 v[138:139], v217 offset:5632
	v_mfma_f32_32x32x16_bf16 v[80:95], v[172:175], v[104:107], v[80:95]
	v_exp_f32_e32 v60, v60
	v_add_f32_e32 v213, v44, v213
	ds_read_b64_tr_b16 v[128:129], v217 offset:6144
	v_exp_f32_e32 v61, v61
	v_add_f32_e32 v213, v45, v213
	ds_read_b64_tr_b16 v[130:131], v217 offset:6656
	v_mfma_f32_32x32x16_bf16 v[64:79], v[168:171], v[104:107], v[64:79]
	v_exp_f32_e32 v62, v62
	v_add_f32_e32 v213, v46, v213
	ds_read_b64_tr_b16 v[120:121], v217 offset:7168
	v_exp_f32_e32 v63, v63
	v_add_f32_e32 v213, v47, v213
	ds_read_b64_tr_b16 v[122:123], v217 offset:7680
	v_mfma_f32_32x32x16_bf16 v[80:95], v[164:167], v[100:103], v[80:95]
	v_add_f32_e32 v237, v48, v49
	v_add_f32_e32 v237, v50, v237
	v_add_f32_e32 v237, v51, v237
	v_add_f32_e32 v237, v52, v237
	v_add_f32_e32 v237, v53, v237
	v_add_f32_e32 v237, v54, v237
	v_add_f32_e32 v237, v55, v237
	v_add_f32_e32 v237, v56, v237
	v_mfma_f32_32x32x16_bf16 v[64:79], v[160:163], v[100:103], v[64:79]
	v_add_f32_e32 v237, v57, v237
	v_add_f32_e32 v237, v58, v237
	v_add_f32_e32 v237, v59, v237
	v_add_f32_e32 v237, v60, v237
	v_add_f32_e32 v237, v61, v237
	v_add_f32_e32 v237, v62, v237
	v_add_f32_e32 v237, v63, v237
	v_add_f32_e32 v213, v237, v213
	v_mfma_f32_32x32x16_bf16 v[80:95], v[156:159], v[96:99], v[80:95]
	v_cvt_pk_bf16_f32 v32, v32, v33
	v_cvt_pk_bf16_f32 v33, v34, v35
	v_cvt_pk_bf16_f32 v34, v36, v37
	v_cvt_pk_bf16_f32 v35, v38, v39
	v_cvt_pk_bf16_f32 v36, v40, v41
	v_cvt_pk_bf16_f32 v37, v42, v43
	v_cvt_pk_bf16_f32 v38, v44, v45
	v_cvt_pk_bf16_f32 v39, v46, v47
	v_mfma_f32_32x32x16_bf16 v[64:79], v[152:155], v[96:99], v[64:79]
	v_cvt_pk_bf16_f32 v48, v48, v49
	v_cvt_pk_bf16_f32 v49, v50, v51
	v_cvt_pk_bf16_f32 v50, v52, v53
	v_cvt_pk_bf16_f32 v51, v54, v55
	v_cvt_pk_bf16_f32 v52, v56, v57
	v_cvt_pk_bf16_f32 v53, v58, v59
	v_cvt_pk_bf16_f32 v54, v60, v61
	v_cvt_pk_bf16_f32 v55, v62, v63
	s_waitcnt lgkmcnt(0)
	v_mfma_f32_32x32x16_bf16 v[0:15], v[32:35], v[148:151], v[0:15]
	v_exp_f32_e32 v40, v88
	v_exp_f32_e32 v41, v89
	v_mfma_f32_32x32x16_bf16 v[16:31], v[32:35], v[144:147], v[16:31]
	v_exp_f32_e32 v42, v90
	v_exp_f32_e32 v43, v91
	v_mfma_f32_32x32x16_bf16 v[0:15], v[36:39], v[140:143], v[0:15]
	v_exp_f32_e32 v44, v92
	v_exp_f32_e32 v45, v93
	v_mfma_f32_32x32x16_bf16 v[16:31], v[36:39], v[136:139], v[16:31]
	v_exp_f32_e32 v46, v94
	v_exp_f32_e32 v47, v95
	v_mfma_f32_32x32x16_bf16 v[0:15], v[48:51], v[132:135], v[0:15]
	v_exp_f32_e32 v32, v80
	v_exp_f32_e32 v33, v81
	v_mfma_f32_32x32x16_bf16 v[16:31], v[48:51], v[128:131], v[16:31]
	v_exp_f32_e32 v34, v82
	v_exp_f32_e32 v35, v83
	v_mfma_f32_32x32x16_bf16 v[0:15], v[52:55], v[124:127], v[0:15]
	v_exp_f32_e32 v36, v84
	v_exp_f32_e32 v37, v85
	v_mfma_f32_32x32x16_bf16 v[16:31], v[52:55], v[120:123], v[16:31]
	v_exp_f32_e32 v38, v86
	v_exp_f32_e32 v39, v87
	s_setprio 0
	s_add_i32 s6, s6, 2
	s_barrier
	s_addk_i32 s63, 0x4000
	v_lshl_add_u64 v[220:221], v[220:221], 0, s[12:13]
	v_lshl_add_u64 v[222:223], v[222:223], 0, s[10:11]
	v_lshl_add_u64 v[224:225], v[224:225], 0, s[10:11]
	s_and_b64 vcc, exec, s[58:59]
	s_cbranch_vccnz .LBB0_597
	s_mov_b32 s68, s70
	s_mov_b32 s70, s71
	s_branch .LBB0_570

; __device__ __forceinline__ void finishSM2(f32x16& p0, f32x16& p1, float alpha, float& l_reg, bf16x8& pa0, bf16x8& pa1, bf16x8& pa2, bf16x8& pa3) {
; #pragma unroll
;   for (int r = 0; r < 16; ++r) p1[r] = __builtin_amdgcn_exp2f(p1[r]);
;   float ps = 0;
; #pragma unroll
;   for (int r = 0; r < 16; ++r) ps += p0[r];
; #pragma unroll
;   for (int r = 0; r < 16; ++r) ps += p1[r];
;   { auto rr = __builtin_amdgcn_permlane32_swap(__float_as_uint(ps), __float_as_uint(ps), false, false);
;     ps = __uint_as_float(rr[0]) + __uint_as_float(rr[1]); }
;   l_reg = l_reg * alpha + ps;
;     ...
;   PK8(p0, 0, pa0); PK8(p0, 8, pa1); PK8(p1, 0, pa2); PK8(p1, 8, pa3);
;     ...
; }
; __device__ __forceinline__ void kload12(bf16x8* kf, const LAS char* Ks, int r32, int hi) {
;   const LAS char* kb = Ks + hi * 1024 + r32 * 16;
; #pragma unroll
;   for (int d0 = 0; d0 < 6; ++d0) { kf[2 * d0] = *(const LAS bf16x8*)(kb + d0 * 2048); kf[2 * d0 + 1] = *(const LAS bf16x8*)(kb + d0 * 2048 + 512); }
; }
; __device__ __forceinline__ void qkt3(f32x16& p0, f32x16& p1, const bf16x8* kf, const bf16x8* qr) {
;   p0 = f32x16{}; p1 = f32x16{};
; #pragma unroll
;   for (int d0 = 0; d0 < 6; ++d0) {
;     p0 = __builtin_amdgcn_mfma_f32_32x32x16_bf16(kf[2 * d0], qr[d0], p0, 0, 0, 0);
;     p1 = __builtin_amdgcn_mfma_f32_32x32x16_bf16(kf[2 * d0 + 1], qr[d0], p1, 0, 0, 0); }
; }
; __device__ __forceinline__ void vload16(s16x4* vf, int vb) {
;   vf[0] = tr_read<0>(vb); vf[1] = tr_read<512>(vb); vf[2] = tr_read<1024>(vb); vf[3] = tr_read<1536>(vb);
;   vf[4] = tr_read<2048>(vb); vf[5] = tr_read<2560>(vb); vf[6] = tr_read<3072>(vb); vf[7] = tr_read<3584>(vb);
;   vf[8] = tr_read<4096>(vb); vf[9] = tr_read<4608>(vb); vf[10] = tr_read<5120>(vb); vf[11] = tr_read<5632>(vb);
;   vf[12] = tr_read<6144>(vb); vf[13] = tr_read<6656>(vb); vf[14] = tr_read<7168>(vb); vf[15] = tr_read<7680>(vb);
; }
; __device__ __forceinline__ void pv3(f32x16* o, const s16x4* vf, bf16x8 pa0, bf16x8 pa1, bf16x8 pa2, bf16x8 pa3) {
;     ...
;   o[0] = __builtin_amdgcn_mfma_f32_32x32x16_bf16(pa0, PKV(0), o[0], 0, 0, 0);
;   o[1] = __builtin_amdgcn_mfma_f32_32x32x16_bf16(pa0, PKV(8), o[1], 0, 0, 0);
;   o[0] = __builtin_amdgcn_mfma_f32_32x32x16_bf16(pa1, PKV(2), o[0], 0, 0, 0);
;   o[1] = __builtin_amdgcn_mfma_f32_32x32x16_bf16(pa1, PKV(10), o[1], 0, 0, 0);
;   o[0] = __builtin_amdgcn_mfma_f32_32x32x16_bf16(pa2, PKV(4), o[0], 0, 0, 0);
.Ljoin_u:
	ds_read_b128 v[48:51], v231 offset:36864
	ds_read_b128 v[52:55], v231 offset:37376
	ds_read_b128 v[188:191], v231 offset:38912
	ds_read_b128 v[184:187], v231 offset:39424
	ds_read_b128 v[180:183], v231 offset:40960
	ds_read_b128 v[176:179], v231 offset:41472
	ds_read_b128 v[172:175], v231 offset:43008
	ds_read_b128 v[168:171], v231 offset:43520
	ds_read_b128 v[164:167], v231 offset:45056
	ds_read_b128 v[160:163], v231 offset:45568
	ds_read_b128 v[156:159], v231 offset:47104
	ds_read_b128 v[152:155], v231 offset:47616
	s_waitcnt vmcnt(0) lgkmcnt(0)
	s_barrier
	s_waitcnt lgkmcnt(0)
	s_setprio 1
	v_mfma_f32_32x32x16_bf16 v[80:95], v[48:51], v[116:119], v[238:253]
	v_exp_f32_e32 v64, v64
	v_add_f32_e32 v213, v32, v213
	ds_read_b64_tr_b16 v[148:149], v233 offset:0
	v_exp_f32_e32 v65, v65
	v_add_f32_e32 v213, v33, v213
	ds_read_b64_tr_b16 v[150:151], v233 offset:512
	v_mfma_f32_32x32x16_bf16 v[48:63], v[52:55], v[116:119], v[238:253]
	v_exp_f32_e32 v66, v66
	v_add_f32_e32 v213, v34, v213
	ds_read_b64_tr_b16 v[140:141], v233 offset:1024
	v_exp_f32_e32 v67, v67
	v_add_f32_e32 v213, v35, v213
	ds_read_b64_tr_b16 v[142:143], v233 offset:1536
	v_mfma_f32_32x32x16_bf16 v[80:95], v[188:191], v[112:115], v[80:95]
	v_exp_f32_e32 v68, v68
	v_add_f32_e32 v213, v36, v213
	ds_read_b64_tr_b16 v[132:133], v233 offset:2048
	v_exp_f32_e32 v69, v69
	v_add_f32_e32 v213, v37, v213
	ds_read_b64_tr_b16 v[134:135], v233 offset:2560
	v_mfma_f32_32x32x16_bf16 v[48:63], v[184:187], v[112:115], v[48:63]
	v_exp_f32_e32 v70, v70
	v_add_f32_e32 v213, v38, v213
	ds_read_b64_tr_b16 v[124:125], v233 offset:3072
	v_exp_f32_e32 v71, v71
	v_add_f32_e32 v213, v39, v213
	ds_read_b64_tr_b16 v[126:127], v233 offset:3584
	v_mfma_f32_32x32x16_bf16 v[80:95], v[180:183], v[108:111], v[80:95]
	v_exp_f32_e32 v72, v72
	v_add_f32_e32 v213, v40, v213
	ds_read_b64_tr_b16 v[144:145], v233 offset:4096
	v_exp_f32_e32 v73, v73
	v_add_f32_e32 v213, v41, v213
	ds_read_b64_tr_b16 v[146:147], v233 offset:4608
	v_mfma_f32_32x32x16_bf16 v[48:63], v[176:179], v[108:111], v[48:63]
	v_exp_f32_e32 v74, v74
	v_add_f32_e32 v213, v42, v213
	ds_read_b64_tr_b16 v[136:137], v233 offset:5120
	v_exp_f32_e32 v75, v75
	v_add_f32_e32 v213, v43, v213
	ds_read_b64_tr_b16 v[138:139], v233 offset:5632
	v_mfma_f32_32x32x16_bf16 v[80:95], v[172:175], v[104:107], v[80:95]
	v_exp_f32_e32 v76, v76
	v_add_f32_e32 v213, v44, v213
	ds_read_b64_tr_b16 v[128:129], v233 offset:6144
	v_exp_f32_e32 v77, v77
	v_add_f32_e32 v213, v45, v213
	ds_read_b64_tr_b16 v[130:131], v233 offset:6656
	v_mfma_f32_32x32x16_bf16 v[48:63], v[168:171], v[104:107], v[48:63]
	v_exp_f32_e32 v78, v78
	v_add_f32_e32 v213, v46, v213
	ds_read_b64_tr_b16 v[120:121], v233 offset:7168
	v_exp_f32_e32 v79, v79
	v_add_f32_e32 v213, v47, v213
	ds_read_b64_tr_b16 v[122:123], v233 offset:7680
	v_mfma_f32_32x32x16_bf16 v[80:95], v[164:167], v[100:103], v[80:95]
	v_add_f32_e32 v237, v64, v65
	v_add_f32_e32 v237, v66, v237
	v_add_f32_e32 v237, v67, v237
	v_add_f32_e32 v237, v68, v237
	v_add_f32_e32 v237, v69, v237
	v_add_f32_e32 v237, v70, v237
	v_add_f32_e32 v237, v71, v237
	v_add_f32_e32 v237, v72, v237
	v_mfma_f32_32x32x16_bf16 v[48:63], v[160:163], v[100:103], v[48:63]
	v_add_f32_e32 v237, v73, v237
	v_add_f32_e32 v237, v74, v237
	v_add_f32_e32 v237, v75, v237
	v_add_f32_e32 v237, v76, v237
	v_add_f32_e32 v237, v77, v237
	v_add_f32_e32 v237, v78, v237
	v_add_f32_e32 v237, v79, v237
	v_add_f32_e32 v213, v237, v213
	v_mfma_f32_32x32x16_bf16 v[80:95], v[156:159], v[96:99], v[80:95]
	v_cvt_pk_bf16_f32 v32, v32, v33
	v_cvt_pk_bf16_f32 v33, v34, v35
	v_cvt_pk_bf16_f32 v34, v36, v37
	v_cvt_pk_bf16_f32 v35, v38, v39
	v_cvt_pk_bf16_f32 v36, v40, v41
	v_cvt_pk_bf16_f32 v37, v42, v43
	v_cvt_pk_bf16_f32 v38, v44, v45
	v_cvt_pk_bf16_f32 v39, v46, v47
	v_mfma_f32_32x32x16_bf16 v[48:63], v[152:155], v[96:99], v[48:63]
	v_cvt_pk_bf16_f32 v64, v64, v65
	v_cvt_pk_bf16_f32 v65, v66, v67
	v_cvt_pk_bf16_f32 v66, v68, v69
	v_cvt_pk_bf16_f32 v67, v70, v71
	v_cvt_pk_bf16_f32 v68, v72, v73
	v_cvt_pk_bf16_f32 v69, v74, v75
	v_cvt_pk_bf16_f32 v70, v76, v77
	v_cvt_pk_bf16_f32 v71, v78, v79
	s_waitcnt lgkmcnt(0)
	v_mfma_f32_32x32x16_bf16 v[0:15], v[32:35], v[148:151], v[0:15]
	v_exp_f32_e32 v40, v88
	v_exp_f32_e32 v41, v89
	v_mfma_f32_32x32x16_bf16 v[16:31], v[32:35], v[144:147], v[16:31]
	v_exp_f32_e32 v42, v90
	v_exp_f32_e32 v43, v91
	v_mfma_f32_32x32x16_bf16 v[0:15], v[36:39], v[140:143], v[0:15]
	v_exp_f32_e32 v44, v92
	v_exp_f32_e32 v45, v93
	v_mfma_f32_32x32x16_bf16 v[16:31], v[36:39], v[136:139], v[16:31]
	v_exp_f32_e32 v46, v94
	v_exp_f32_e32 v47, v95
	v_mfma_f32_32x32x16_bf16 v[0:15], v[64:67], v[132:135], v[0:15]
	v_exp_f32_e32 v32, v80
	v_exp_f32_e32 v33, v81
	v_mfma_f32_32x32x16_bf16 v[16:31], v[64:67], v[128:131], v[16:31]
	v_exp_f32_e32 v34, v82
	v_exp_f32_e32 v35, v83
	v_mfma_f32_32x32x16_bf16 v[0:15], v[68:71], v[124:127], v[0:15]
	v_exp_f32_e32 v36, v84
	v_exp_f32_e32 v37, v85
	v_mfma_f32_32x32x16_bf16 v[16:31], v[68:71], v[120:123], v[16:31]
	v_exp_f32_e32 v38, v86
	v_exp_f32_e32 v39, v87
	s_setprio 0
	s_barrier
	s_and_b64 vcc, exec, s[4:5]
	s_cbranch_vccnz .LBB0_603
	s_barrier

; __device__ __forceinline__ void xcd_barrier(const XcdBarrier& b) {
;     asm volatile("s_waitcnt vmcnt(0)" ::: "memory");
;     __syncthreads();
;     if (threadIdx.x == 0) {
;         unsigned* bar = b.bar;
;         __builtin_amdgcn_s_waitcnt(0);
;         unsigned nloc = b.st[0], nx = b.st[1];
;         if (nloc == 0u) { xcd_barrier_complete(bar, b.x, nloc, nx); b.st[0] = nloc; b.st[1] = nx; }
.LBB0_606:
	s_nop 0
	s_nop 0
	s_nop 0
	s_nop 0
	s_nop 0
	s_nop 0
	s_nop 0
	s_nop 0
	s_nop 0
	s_nop 0
	s_nop 0
	s_nop 0
	s_cmp_gt_i32 s31, 4
	s_cselect_b64 s[2:3], -1, 0
	s_and_b64 s[0:1], s[0:1], s[2:3]
	s_andn2_b64 vcc, exec, s[0:1]
	s_cbranch_vccnz .LBB0_660
	s_waitcnt vmcnt(0)
	s_waitcnt vmcnt(0) lgkmcnt(0)
	s_barrier
	s_and_saveexec_b64 s[0:1], s[82:83]
	s_cbranch_execz .LBB0_659
	s_add_i32 s4, 0, 0x22000
	v_mov_b32_e32 v0, s4
	s_waitcnt vmcnt(0) expcnt(0) lgkmcnt(0)
	ds_read_b32 v2, v0
	s_add_i32 s4, 0, 0x22004
	v_mov_b32_e32 v0, s4
	ds_read_b32 v0, v0
	s_waitcnt lgkmcnt(1)
	v_cmp_ne_u32_e32 vcc, 0, v2
	s_cbranch_vccnz .LBB0_623
	v_readlane_b32 s4, v254, 0
	s_mul_i32 s18, s93, s4
	s_add_u32 s4, s28, 0x1000
	s_addc_u32 s5, s29, 0
	s_add_u32 s6, s28, 0x1100
	s_addc_u32 s7, s29, 0
	s_add_u32 s8, s28, 0x1200
	s_addc_u32 s9, s29, 0
	s_add_u32 s10, s28, 0x1300
	s_mul_i32 s18, s18, s92
	s_addc_u32 s11, s29, 0
	s_mov_b32 s19, 1
	v_mov_b32_e32 v16, 0
	s_branch .LBB0_611
